# speedup vs baseline: 1.0125x; 1.0048x over previous
; #define LAS __attribute__((address_space(3)))
; #define tid fresh_tid(wid1)
; template <bool DIFF>
; __device__ __forceinline__ void attn_item(const Params& p, int l, int I, LAS unsigned char* lds, const int tid) {
;     ...
;     auto keyrow = [&](int t) { return t < 4 ? ctxbase + 64 * t : latbase + 64 * (t - 4); };
;     auto gload = [&](int t, const int j) {
;         const int kr0 = keyrow(t);
;         if (DIFF) { g0[j] = *(const u32x4*)(DKb + (size_t)(kr0 + rowq) * 512 + 64 * h + 8 * cq8); g1[j] = *(const u32x4*)(DVb + (size_t)(kr0 + rowk) * 512 + 64 * h + 8 * c8); }
;         else { g0[j] = *(const u32x4*)(KVb + (size_t)(kr0 + rowq) * 1024 + 128 * h + 8 * cq8); g1[j] = *(const u32x4*)(KVb + (size_t)(kr0 + rowk) * 1024 + 128 * h + 64 + 8 * c8);
;             if (tid < 256) g2[j] = *(const u32x4*)(KRb + (size_t)(kr0 + rowr) * 32 + 8 * cr4); }
;     };
;     auto lwrite = [&](int slot, const int j) {
;         LAS unsigned char* sb = lds + slot * AT_SLOT + j * AT_SUB;
;         *(LAS u32x4*)(sb + kw0) = g0[j]; *(LAS u32x4*)(sb + vw) = g1[j];
;         if (!DIFF) { if (tid < 256) *(LAS u32x4*)(sb + kw2) = g2[j]; }
;     };
;     LAS float* scr = (LAS float*)(lds + AT_SCR + wid * 512);
;     float mref1 = 0.f, l1 = 0.f, mref2 = 0.f, l2 = 0.f;
;     f32x16 o1[2], o2[2];
;     float zf = 0.f; asm volatile("" : "+v"(zf));
; #pragma unroll
;     for (int r = 0; r < 16; ++r) { o1[0][r] = zf; o1[1][r] = zf; o2[0][r] = zf; o2[1][r] = zf; }
;     const float sc = (DIFF ? 0.17677669529663687f : 0.10206207261596575f) * LOG2E;
; #pragma unroll
;     for (int d0 = 0; d0 < (DIFF ? 4 : 6); ++d0) qf[d0] = scale_bf8(qf[d0], sc);
;     f32x16 negm1, negm2;
; #pragma unroll
;     for (int r = 0; r < 16; ++r) { negm1[r] = zf; negm2[r] = zf; }
;     const unsigned vlane = ((lane >> 4) & 1) * 32 + (lane & 3) * 8 + (4 * hi + ((lane & 15) >> 2)) * 64;
;     gload(0, 0); gload(1, 1); lwrite(0, 0); lwrite(0, 1);
;     __syncthreads();
;     for (int st = 0; st < nt / 2; ++st) {
;         const bool more = (2 * st + 2 < nt);
;         if (more) { gload(2 * st + 2, 0); gload(2 * st + 3, 1); }
.LBB0_456:
	s_or_b64 exec, exec, s[24:25]
	v_add_f32_e32 v67, 0, v98
	v_add_f32_e32 v50, 0, v50
	v_add_f32_e32 v67, v99, v67
	v_add_f32_e32 v50, v51, v50
	v_add_f32_e32 v51, v100, v67
	v_add_f32_e32 v50, v52, v50
	v_add_f32_e32 v51, v101, v51
	v_add_f32_e32 v50, v53, v50
	v_add_f32_e32 v51, v102, v51
	v_add_f32_e32 v50, v54, v50
	v_add_f32_e32 v51, v103, v51
	v_add_f32_e32 v50, v55, v50
	v_add_f32_e32 v51, v104, v51
	v_add_f32_e32 v50, v56, v50
	v_add_f32_e32 v51, v105, v51
	v_add_f32_e32 v50, v57, v50
	v_add_f32_e32 v42, v42, v51
	v_add_f32_e32 v50, v58, v50
	v_add_f32_e32 v42, v43, v42
	v_add_f32_e32 v43, v59, v50
	v_add_f32_e32 v42, v44, v42
	v_add_f32_e32 v43, v60, v43
	v_add_f32_e32 v42, v45, v42
	v_add_f32_e32 v43, v61, v43
	v_add_f32_e32 v42, v46, v42
	v_add_f32_e32 v43, v62, v43
	v_add_f32_e32 v42, v47, v42
	v_add_f32_e32 v43, v63, v43
	v_add_f32_e32 v42, v48, v42
	v_add_f32_e32 v43, v64, v43
	v_add_f32_e32 v42, v49, v42
	v_add_f32_e32 v43, v65, v43
	v_lshl_add_u64 v[198:199], s[22:23], 0, v[192:193]
	s_add_i32 s22, s34, s37
	v_add_f32_e32 v42, v43, v42
	v_add_u32_e32 v192, s22, v111
	s_add_i32 s22, s34, s36
	v_add_f32_e32 v225, v33, v42
	v_add_u32_e32 v33, 0, v66
	v_add_u32_e32 v224, s22, v111
	s_lshl_b32 s22, s30, 6
	ds_write_b128 v33, v[34:37] offset:61440
	v_add_u32_e32 v33, 0, v164
	v_add_u32_e32 v223, s34, v110
	s_and_b32 s34, s22, 0x3f80
	ds_write_b128 v33, v[38:41] offset:61440
	s_mov_b32 s35, 1
	s_addk_i32 s34, 0xff80
	s_mov_b32 s36, 0
	s_mov_b32 s37, 4
	v_mov_b32_e32 v33, v32
	v_mov_b32_e32 v34, v32
	v_mov_b32_e32 v35, v32
	v_mov_b32_e32 v36, v32
	v_mov_b32_e32 v37, v32
	v_mov_b32_e32 v38, v32
	v_mov_b32_e32 v39, v32
	v_mov_b32_e32 v40, v32
	v_mov_b32_e32 v41, v32
	v_mov_b32_e32 v42, v32
	v_mov_b32_e32 v43, v32
	v_mov_b32_e32 v44, v32
	v_mov_b32_e32 v45, v32
	v_mov_b32_e32 v46, v32
	v_mov_b32_e32 v47, v32
	v_lshlrev_b32_e32 v212, 11, v224
	v_mov_b32_e32 v213, 0
	v_lshl_add_u64 v[212:213], v[194:195], 0, v[212:213]
	v_lshlrev_b32_e32 v214, 11, v223
	v_mov_b32_e32 v215, 0
	v_lshl_add_u64 v[214:215], v[198:199], 0, v[214:215]
	s_waitcnt lgkmcnt(0)
	s_barrier
	s_branch .LBB0_459

; #define tid fresh_tid(wid1)
; template <bool DIFF>
; __device__ __forceinline__ void attn_item(const Params& p, int l, int I, LAS unsigned char* lds, const int tid) {
;     ...
;     auto keyrow = [&](int t) { return t < 4 ? ctxbase + 64 * t : latbase + 64 * (t - 4); };
;     auto gload = [&](int t, const int j) {
;         const int kr0 = keyrow(t);
;         if (DIFF) { g0[j] = *(const u32x4*)(DKb + (size_t)(kr0 + rowq) * 512 + 64 * h + 8 * cq8); g1[j] = *(const u32x4*)(DVb + (size_t)(kr0 + rowk) * 512 + 64 * h + 8 * c8); }
;         else { g0[j] = *(const u32x4*)(KVb + (size_t)(kr0 + rowq) * 1024 + 128 * h + 8 * cq8); g1[j] = *(const u32x4*)(KVb + (size_t)(kr0 + rowk) * 1024 + 128 * h + 64 + 8 * c8);
;             if (tid < 256) g2[j] = *(const u32x4*)(KRb + (size_t)(kr0 + rowr) * 32 + 8 * cr4); }
;     };
.LBB0_459:
	s_cmp_lt_u32 s37, s30
	s_cselect_b64 s[22:23], -1, 0
	s_cmp_ge_u32 s37, s30
	s_cbranch_scc1 .LBB0_465
	s_lshl_b32 s24, s36, 11
	s_mov_b32 s25, 0
	v_lshl_add_u64 v[48:49], v[212:213], 0, s[24:25]
	v_lshl_add_u64 v[50:51], v[214:215], 0, s[24:25]
	global_load_dwordx4 v[120:123], v[48:49], off
	global_load_dwordx4 v[124:127], v[50:51], off offset:128
	s_and_saveexec_b64 s[24:25], s[6:7]
	s_cbranch_execz .LBB0_462
	v_add_u32_e32 v52, s36, v192
	v_ashrrev_i32_e32 v53, 31, v52
	v_lshlrev_b64 v[52:53], 6, v[52:53]
	v_lshl_add_u64 v[52:53], v[196:197], 0, v[52:53]
	global_load_dwordx4 v[112:115], v[52:53], off
.LBB0_462:
	s_or_b64 exec, exec, s[24:25]
	s_add_i32 s24, s36, 64
	s_lshl_b32 s24, s24, 11
	s_mov_b32 s25, 0
	v_lshl_add_u64 v[48:49], v[212:213], 0, s[24:25]
	v_lshl_add_u64 v[50:51], v[214:215], 0, s[24:25]
	global_load_dwordx4 v[132:135], v[48:49], off
	global_load_dwordx4 v[136:139], v[50:51], off offset:128
	s_and_saveexec_b64 s[24:25], s[6:7]
	s_cbranch_execz .LBB0_464
	v_add3_u32 v48, v192, s36, 64
	v_ashrrev_i32_e32 v49, 31, v48
	v_lshlrev_b64 v[48:49], 6, v[48:49]
	v_lshl_add_u64 v[48:49], v[196:197], 0, v[48:49]
	global_load_dwordx4 v[116:119], v[48:49], off

; #define tid fresh_tid(wid1)
; template <bool DIFF>
; __device__ __forceinline__ void attn_item(const Params& p, int l, int I, LAS unsigned char* lds, const int tid) {
;     ...
;     const int qrow = qrow0 + 32 * wid + r32;
;     bf16x8 qf[DIFF ? 4 : 6];
;     if (DIFF) {
;         const bf16_t* qp = DQb + (size_t)qrow * 512 + 64 * h + 8 * hi;
;         qf[0] = *(const bf16x8*)(qp); qf[1] = *(const bf16x8*)(qp + 16); qf[2] = *(const bf16x8*)(qp + 32); qf[3] = *(const bf16x8*)(qp + 48);
;     } else {
;         const bf16_t* qp = Qb + (size_t)qrow * 768 + 96 * h + 8 * hi;
; #pragma unroll
;         for (int d0 = 0; d0 < 6; ++d0) qf[d0] = *(const bf16x8*)(qp + 16 * d0);
;     }
;     const int rowk = tid >> 3, c8 = tid & 7;
;     const int rowq = (lane & 15) + 16 * (wid & 3), cq8 = (lane >> 4) + 4 * (wid >> 2);
;     const int rowr = (lane & 15) + 16 * wid, cr4 = lane >> 4;
;     const unsigned kw0 = cq8 * 1024 + rowq * 16, vw = AT_V + (c8 >> 2) * 4096 + rowk * 64 + (c8 & 3) * 16, kw2 = (8 + cr4) * 1024 + rowr * 16;
;     u32x4 g0[2], g1[2], g2[2];
;     auto keyrow = [&](int t) { return t < 4 ? ctxbase + 64 * t : latbase + 64 * (t - 4); };
;     auto gload = [&](int t, const int j) {
;         const int kr0 = keyrow(t);
;         if (DIFF) { g0[j] = *(const u32x4*)(DKb + (size_t)(kr0 + rowq) * 512 + 64 * h + 8 * cq8); g1[j] = *(const u32x4*)(DVb + (size_t)(kr0 + rowk) * 512 + 64 * h + 8 * c8); }
;         else { g0[j] = *(const u32x4*)(KVb + (size_t)(kr0 + rowq) * 1024 + 128 * h + 8 * cq8); g1[j] = *(const u32x4*)(KVb + (size_t)(kr0 + rowk) * 1024 + 128 * h + 64 + 8 * c8);
;             if (tid < 256) g2[j] = *(const u32x4*)(KRb + (size_t)(kr0 + rowr) * 32 + 8 * cr4); }
;     };
;     auto lwrite = [&](int slot, const int j) {
;         LAS unsigned char* sb = lds + slot * AT_SLOT + j * AT_SUB;
;         *(LAS u32x4*)(sb + kw0) = g0[j]; *(LAS u32x4*)(sb + vw) = g1[j];
;         if (!DIFF) { if (tid < 256) *(LAS u32x4*)(sb + kw2) = g2[j]; }
;     };
;     LAS float* scr = (LAS float*)(lds + AT_SCR + wid * 512);
;     float mref1 = 0.f, l1 = 0.f, mref2 = 0.f, l2 = 0.f;
;     f32x16 o1[2], o2[2];
;     float zf = 0.f; asm volatile("" : "+v"(zf));
; #pragma unroll
;     for (int r = 0; r < 16; ++r) { o1[0][r] = zf; o1[1][r] = zf; o2[0][r] = zf; o2[1][r] = zf; }
;     const float sc = (DIFF ? 0.17677669529663687f : 0.10206207261596575f) * LOG2E;
; #pragma unroll
.LBB0_491:
	s_and_b32 s4, s25, 0xffffe000
	s_sub_i32 s30, s4, 64
	s_mov_b32 s4, 0
	s_and_b32 s37, s26, 0xffffff00
	v_mbcnt_lo_u32_b32 v0, -1, s4
	v_mbcnt_hi_u32_b32 v169, -1, v0
	v_add_u32_e32 v4, s24, v169
	s_add_i32 s31, s37, 0x8000
	v_readfirstlane_b32 s4, v4
	s_ashr_i32 s29, s4, 6
	s_lshl_b32 s4, s26, 5
	s_and_b32 s36, s4, 0xffffe000
	s_and_b32 s18, s4, 0xffffff00
	s_mov_b32 s4, 30
	s_mov_b32 s4, 30
	s_mov_b32 s4, 30
	s_mov_b32 s4, 30
	s_ashr_i32 s5, s4, 31
	s_lshl_b64 s[4:5], s[4:5], 3
	s_add_u32 s4, s0, s4
	s_addc_u32 s5, s1, s5
	s_load_dwordx2 s[4:5], s[4:5], 0x0
	s_mov_b32 s8, 30
	v_and_b32_e32 v170, 31, v169
	v_bfe_u32 v171, v169, 5, 1
	v_lshlrev_b32_e32 v192, 4, v171
	s_waitcnt lgkmcnt(0)
	s_add_u32 s6, s4, 0x4000000
	s_mov_b32 s4, 30
	s_addc_u32 s7, s5, 0
	s_ashr_i32 s5, s4, 31
	s_lshl_b64 s[4:5], s[4:5], 3
	s_add_u32 s4, s0, s4
	s_addc_u32 s5, s1, s5
	s_load_dwordx2 s[4:5], s[4:5], 0x0
	s_ashr_i32 s9, s8, 31
	s_lshl_b64 s[8:9], s[8:9], 3
	s_add_u32 s8, s0, s8
	s_addc_u32 s9, s1, s9
	s_lshl_b32 s27, s29, 5
	s_add_i32 s27, s27, s18
	v_or_b32_e32 v0, s27, v170
	v_ashrrev_i32_e32 v1, 31, v0
	s_lshl_b32 s18, s26, 6
	v_lshlrev_b64 v[0:1], 10, v[0:1]
	s_and_b32 s28, s18, 0x1c0
	v_lshl_add_u64 v[0:1], s[6:7], 0, v[0:1]
	s_lshl_b32 s78, s28, 1
	v_lshl_add_u64 v[0:1], v[0:1], 0, s[78:79]
	s_mov_b32 s19, 30
	v_lshl_add_u64 v[2:3], v[0:1], 0, v[192:193]
	s_load_dwordx2 s[8:9], s[8:9], 0x0
	global_load_dwordx4 v[16:19], v[2:3], off
	global_load_dwordx4 v[20:23], v[2:3], off offset:32
	global_load_dwordx4 v[24:27], v[2:3], off offset:64
	global_load_dwordx4 v[28:31], v[2:3], off offset:96
	s_lshl_b32 s18, s29, 4
	s_lshl_b32 s19, s29, 9
	v_ashrrev_i32_e32 v172, 3, v4
	s_waitcnt lgkmcnt(0)
	s_add_u32 s4, s4, 0x11050000
	v_bfe_u32 v5, v169, 4, 2
	v_lshlrev_b32_e32 v6, 10, v169
	v_add_u32_e32 v4, s31, v172
	s_addc_u32 s5, s5, 0
	v_and_b32_e32 v41, 0x1000, v6
	v_and_or_b32 v6, s29, -4, v5
	v_ashrrev_i32_e32 v5, 31, v4
	s_add_u32 s8, s8, 0x13150000
	v_lshlrev_b64 v[32:33], 10, v[4:5]
	s_addc_u32 s9, s9, 0
	v_and_b32_e32 v37, 7, v169
	v_lshl_add_u64 v[32:33], s[8:9], 0, v[32:33]
	v_and_b32_e32 v1, 15, v169
	v_lshl_add_u64 v[32:33], v[32:33], 0, s[78:79]
	v_lshlrev_b32_e32 v38, 4, v37
	v_mov_b32_e32 v39, v193
	v_mov_b32_e32 v0, v193
	v_and_or_b32 v173, s18, 48, v1
	v_lshl_add_u64 v[32:33], v[32:33], 0, v[38:39]
	s_add_i32 s18, s37, 0x8040
	global_load_dwordx4 v[100:103], v[32:33], off
	v_or_b32_e32 v32, s18, v173
	v_ashrrev_i32_e32 v33, 31, v32
	v_lshlrev_b32_e32 v42, 10, v6
	v_lshlrev_b32_e32 v6, 3, v6
	v_lshlrev_b64 v[32:33], 10, v[32:33]
	v_ashrrev_i32_e32 v7, 31, v6
	v_lshl_add_u64 v[32:33], s[4:5], 0, v[32:33]
	v_lshlrev_b64 v[34:35], 1, v[6:7]
	v_or_b32_e32 v4, s31, v173
	v_lshl_add_u64 v[32:33], v[32:33], 0, s[78:79]
	v_ashrrev_i32_e32 v5, 31, v4
	v_lshl_add_u64 v[32:33], v[32:33], 0, v[34:35]
	v_lshlrev_b64 v[4:5], 10, v[4:5]
	global_load_dwordx4 v[108:111], v[32:33], off
	v_add_u32_e32 v32, s18, v172
	v_lshl_add_u64 v[4:5], s[4:5], 0, v[4:5]
	v_ashrrev_i32_e32 v33, 31, v32
	v_lshl_add_u64 v[4:5], v[4:5], 0, s[78:79]
	v_lshlrev_b64 v[32:33], 10, v[32:33]
	v_lshl_add_u64 v[4:5], v[4:5], 0, v[34:35]
	v_lshl_add_u64 v[32:33], s[8:9], 0, v[32:33]
	global_load_dwordx4 v[96:99], v[4:5], off
	v_lshl_add_u64 v[32:33], v[32:33], 0, s[78:79]
	v_lshl_add_u64 v[32:33], v[32:33], 0, v[38:39]
	global_load_dwordx4 v[116:119], v[32:33], off
	s_add_i32 s35, s19, 0
	s_add_i32 s35, s35, 0x14000
	s_add_u32 s4, s4, s78
	v_lshlrev_b32_e32 v40, 4, v169
	s_addc_u32 s5, s5, 0
	v_lshl_or_b32 v174, v173, 4, v42
	v_lshl_add_u64 v[164:165], s[4:5], 0, v[34:35]
	s_add_u32 s4, s8, s78
	v_mov_b32_e32 v14, v0
	v_mov_b32_e32 v15, v0
	s_addc_u32 s5, s9, 0
	v_and_b32_e32 v168, 63, v169
	v_mov_b32_e32 v1, v0
	v_mov_b32_e32 v2, v0
	v_mov_b32_e32 v3, v0
	v_mov_b32_e32 v4, v0
	v_mov_b32_e32 v5, v0
	v_mov_b32_e32 v6, v0
	v_mov_b32_e32 v7, v0
	v_mov_b32_e32 v8, v0
	v_mov_b32_e32 v9, v0
	v_mov_b32_e32 v10, v0
	v_mov_b32_e32 v11, v0
	v_mov_b32_e32 v12, v0
	v_mov_b32_e32 v13, v0
	s_waitcnt vmcnt(7)
	v_lshlrev_b32_e32 v36, 16, v16
	v_and_b32_e32 v37, 0xffff0000, v16
	v_lshlrev_b32_e32 v16, 16, v17
	v_and_b32_e32 v17, 0xffff0000, v17
	v_pk_mul_f32 v[16:17], v[16:17], s[74:75] op_sel_hi:[1,0]
	v_pk_mul_f32 v[32:33], v[36:37], s[74:75] op_sel_hi:[1,0]
	v_cvt_pk_bf16_f32 v105, v16, v17
	v_lshlrev_b32_e32 v16, 16, v18
	v_and_b32_e32 v17, 0xffff0000, v18
	v_pk_mul_f32 v[16:17], v[16:17], s[74:75] op_sel_hi:[1,0]
	v_cvt_pk_bf16_f32 v104, v32, v33
	v_cvt_pk_bf16_f32 v106, v16, v17
	v_lshlrev_b32_e32 v16, 16, v19
	v_and_b32_e32 v17, 0xffff0000, v19
	v_pk_mul_f32 v[16:17], v[16:17], s[74:75] op_sel_hi:[1,0]
	v_and_b32_e32 v178, 0xc0, v40
	v_cvt_pk_bf16_f32 v107, v16, v17
	s_waitcnt vmcnt(6)
; #define LAS __attribute__((address_space(3)))
; template <bool DIFF>
; __device__ __forceinline__ void attn_item(const Params& p, int l, int I, LAS unsigned char* lds, const int tid) {
;     ...
;     LAS float* scr = (LAS float*)(lds + AT_SCR + wid * 512);
;     float mref1 = 0.f, l1 = 0.f, mref2 = 0.f, l2 = 0.f;
;     f32x16 o1[2], o2[2];
;     float zf = 0.f; asm volatile("" : "+v"(zf));
; #pragma unroll
;     for (int r = 0; r < 16; ++r) { o1[0][r] = zf; o1[1][r] = zf; o2[0][r] = zf; o2[1][r] = zf; }
;     const float sc = (DIFF ? 0.17677669529663687f : 0.10206207261596575f) * LOG2E;
; #pragma unroll
;     for (int d0 = 0; d0 < (DIFF ? 4 : 6); ++d0) qf[d0] = scale_bf8(qf[d0], sc);
;     f32x16 negm1, negm2;
; #pragma unroll
;     for (int r = 0; r < 16; ++r) { negm1[r] = zf; negm2[r] = zf; }
;     const unsigned vlane = ((lane >> 4) & 1) * 32 + (lane & 3) * 8 + (4 * hi + ((lane & 15) >> 2)) * 64;
;     gload(0, 0); gload(1, 1); lwrite(0, 0); lwrite(0, 1);
	v_lshlrev_b32_e32 v16, 16, v20
	v_and_b32_e32 v17, 0xffff0000, v20
	v_pk_mul_f32 v[16:17], v[16:17], s[74:75] op_sel_hi:[1,0]
	v_lshl_add_u64 v[166:167], s[4:5], 0, v[38:39]
	v_cvt_pk_bf16_f32 v112, v16, v17
	v_lshlrev_b32_e32 v16, 16, v21
	v_and_b32_e32 v17, 0xffff0000, v21
	v_pk_mul_f32 v[16:17], v[16:17], s[74:75] op_sel_hi:[1,0]
	v_mov_b64_e32 v[62:63], v[14:15]
	v_cvt_pk_bf16_f32 v113, v16, v17
	v_lshlrev_b32_e32 v16, 16, v22
	v_and_b32_e32 v17, 0xffff0000, v22
	v_pk_mul_f32 v[16:17], v[16:17], s[74:75] op_sel_hi:[1,0]
	s_mov_b32 s34, 0
	v_cvt_pk_bf16_f32 v114, v16, v17
	v_lshlrev_b32_e32 v16, 16, v23
	v_and_b32_e32 v17, 0xffff0000, v23
	v_pk_mul_f32 v[16:17], v[16:17], s[74:75] op_sel_hi:[1,0]
	v_lshlrev_b32_e32 v177, 8, v171
	v_cvt_pk_bf16_f32 v115, v16, v17
	s_waitcnt vmcnt(5)
	v_lshlrev_b32_e32 v16, 16, v24
	v_and_b32_e32 v17, 0xffff0000, v24
	v_pk_mul_f32 v[16:17], v[16:17], s[74:75] op_sel_hi:[1,0]
	v_lshlrev_b32_e32 v181, 10, v171
	v_cvt_pk_bf16_f32 v120, v16, v17
	v_lshlrev_b32_e32 v16, 16, v25
	v_and_b32_e32 v17, 0xffff0000, v25
	v_pk_mul_f32 v[16:17], v[16:17], s[74:75] op_sel_hi:[1,0]
	v_lshlrev_b32_e32 v182, 4, v170
	v_cvt_pk_bf16_f32 v121, v16, v17
	v_lshlrev_b32_e32 v16, 16, v26
	v_and_b32_e32 v17, 0xffff0000, v26
	v_pk_mul_f32 v[16:17], v[16:17], s[74:75] op_sel_hi:[1,0]
	v_cmp_gt_u32_e64 s[4:5], 32, v168
	v_cvt_pk_bf16_f32 v122, v16, v17
	v_lshlrev_b32_e32 v16, 16, v27
	v_and_b32_e32 v17, 0xffff0000, v27
	v_pk_mul_f32 v[16:17], v[16:17], s[74:75] op_sel_hi:[1,0]
	v_lshl_add_u32 v180, v170, 2, s35
	v_cvt_pk_bf16_f32 v123, v16, v17
	s_waitcnt vmcnt(4)
	v_lshlrev_b32_e32 v16, 16, v28
	v_and_b32_e32 v17, 0xffff0000, v28
	v_pk_mul_f32 v[16:17], v[16:17], s[74:75] op_sel_hi:[1,0]
	s_addk_i32 s36, 0xff00
	v_cvt_pk_bf16_f32 v124, v16, v17
	v_lshlrev_b32_e32 v16, 16, v29
	v_and_b32_e32 v17, 0xffff0000, v29
	v_pk_mul_f32 v[16:17], v[16:17], s[74:75] op_sel_hi:[1,0]
	s_add_i32 s37, s37, 0x80c0
	v_cvt_pk_bf16_f32 v125, v16, v17
	v_lshlrev_b32_e32 v16, 16, v30
	v_and_b32_e32 v17, 0xffff0000, v30
	v_pk_mul_f32 v[16:17], v[16:17], s[74:75] op_sel_hi:[1,0]
	v_add_u32_e32 v183, 0x80, v172
	v_cvt_pk_bf16_f32 v126, v16, v17
	v_lshlrev_b32_e32 v16, 16, v31
	v_and_b32_e32 v17, 0xffff0000, v31
	v_pk_mul_f32 v[16:17], v[16:17], s[74:75] op_sel_hi:[1,0]
	v_or_b32_e32 v184, 0x80, v173
	v_cvt_pk_bf16_f32 v127, v16, v17
	v_lshlrev_b32_e32 v16, 1, v169
	v_lshl_add_u32 v17, v172, 6, v41
	v_and_b32_e32 v175, 32, v16
	v_lshlrev_b32_e32 v16, 3, v169
	v_and_or_b32 v179, v40, 48, v17
	v_and_b32_e32 v176, 24, v16
	v_add_u32_e32 v16, 0, v174
	v_add_u32_e32 v17, 0, v179
	s_waitcnt vmcnt(1)
	ds_write_b128 v16, v[96:99]
	ds_write_b128 v17, v[100:103] offset:12288
	ds_write_b128 v16, v[108:111] offset:20480
	s_waitcnt vmcnt(0)
	ds_write_b128 v17, v[116:119] offset:32768
	v_mov_b64_e32 v[30:31], v[14:15]
	v_mov_b64_e32 v[46:47], v[14:15]
	v_mov_b32_e32 v161, 0
	v_mov_b64_e32 v[28:29], v[12:13]
	v_mov_b64_e32 v[26:27], v[10:11]
	v_mov_b64_e32 v[24:25], v[8:9]
	v_mov_b64_e32 v[22:23], v[6:7]
	v_mov_b64_e32 v[20:21], v[4:5]
	v_mov_b64_e32 v[18:19], v[2:3]
	v_mov_b64_e32 v[16:17], v[0:1]
	v_mov_b64_e32 v[44:45], v[12:13]
	v_mov_b64_e32 v[42:43], v[10:11]
	v_mov_b64_e32 v[40:41], v[8:9]
	v_mov_b64_e32 v[38:39], v[6:7]
	v_mov_b64_e32 v[36:37], v[4:5]
	v_mov_b64_e32 v[34:35], v[2:3]
	v_mov_b64_e32 v[32:33], v[0:1]
	v_mov_b64_e32 v[60:61], v[12:13]
	v_mov_b64_e32 v[58:59], v[10:11]
	v_mov_b64_e32 v[56:57], v[8:9]
	v_mov_b64_e32 v[54:55], v[6:7]
	v_mov_b64_e32 v[52:53], v[4:5]
	v_mov_b64_e32 v[50:51], v[2:3]
	v_mov_b64_e32 v[48:49], v[0:1]
	v_add_u32_e32 v181, v181, v182
	v_add3_u32 v184, v175, v176, v177
	v_add_u32_e32 v184, v184, v178
	v_mov_b32_e32 v178, v174
	v_lshlrev_b32_e32 v176, 10, v173
	v_mov_b32_e32 v177, 0
	v_lshl_add_u64 v[176:177], v[164:165], 0, v[176:177]
	v_lshlrev_b32_e32 v182, 10, v172
	v_mov_b32_e32 v183, 0
	v_lshl_add_u64 v[182:183], v[166:167], 0, v[182:183]
	v_mov_b32_e32 v194, 0
	v_mov_b32_e32 v195, 0
	v_mov_b32_e32 v196, 0
	v_mov_b32_e32 v197, 0
	v_mov_b32_e32 v198, 0
	v_mov_b32_e32 v199, 0
	v_mov_b32_e32 v200, 0
	v_mov_b32_e32 v201, 0
	v_mov_b32_e32 v202, 0
	v_mov_b32_e32 v203, 0
	v_mov_b32_e32 v204, 0
	v_mov_b32_e32 v205, 0
	v_mov_b32_e32 v206, 0
	v_mov_b32_e32 v207, 0
	v_mov_b32_e32 v208, 0
	v_mov_b32_e32 v209, 0
	v_mov_b32_e32 v218, 0
	v_mov_b32_e32 v219, 0
	v_mov_b32_e32 v220, 0
	v_mov_b32_e32 v221, 0
	v_mov_b32_e32 v222, 0
	v_mov_b32_e32 v223, 0
	v_mov_b32_e32 v224, 0
	v_mov_b32_e32 v225, 0
	v_mov_b32_e32 v226, 0
	v_mov_b32_e32 v227, 0
	v_mov_b32_e32 v228, 0
	v_mov_b32_e32 v229, 0
	v_mov_b32_e32 v230, 0
	v_mov_b32_e32 v231, 0
	v_mov_b32_e32 v232, 0
	v_mov_b32_e32 v233, 0
	v_mov_b32_e32 v164, 0
	v_mov_b32_e32 v165, 0
	v_mov_b32_e32 v166, 0
	v_mov_b32_e32 v167, 0
	v_mov_b32_e32 v172, 0
	v_mov_b32_e32 v173, 0
	v_mov_b32_e32 v174, 0
	v_mov_b32_e32 v175, 0
	v_mov_b32_e32 v214, 0x3f803f80
	v_mov_b32_e32 v215, 0x3f803f80
	v_mov_b32_e32 v185, 0
	v_mov_b32_e32 v162, 0
	v_mov_b32_e32 v186, 0
	s_waitcnt lgkmcnt(0)
	s_barrier
	s_branch .LBB0_493

; __device__ __forceinline__ void softmax_pv(f32x16& s0, f32x16& s1, float& mref, f32x16& negm, float& lsum, f32x16 (&o)[2], LAS float* fac, const bf16x8 (&vf)[2][4], bool first, int r32, int hi) {
;     ...
;     float ps0 = 0.f, ps1 = 0.f;
; #pragma unroll
;     for (int r = 0; r < 16; ++r) { s0[r] = __builtin_amdgcn_exp2f(s0[r]); s1[r] = __builtin_amdgcn_exp2f(s1[r]); ps0 += s0[r]; ps1 += s1[r]; }
;     lsum += ps0 + ps1;
;     bf16x8 pa[4];
; #pragma unroll
;     for (int k = 0; k < 4; ++k) {
;         const f32x16& s = (k < 2) ? s0 : s1; const int rb = 8 * (k & 1);
;         u32x4 w; w.x = cvt_pk_bf16(s[rb + 0], s[rb + 1]); w.y = cvt_pk_bf16(s[rb + 2], s[rb + 3]); w.z = cvt_pk_bf16(s[rb + 4], s[rb + 5]); w.w = cvt_pk_bf16(s[rb + 6], s[rb + 7]);
;         pa[k] = __builtin_bit_cast(bf16x8, w);
;     }
; #pragma unroll
;     for (int k = 0; k < 4; ++k) {
; template <bool DIFF>
; __device__ __forceinline__ void attn_item(const Params& p, int l, int I, LAS unsigned char* lds, const int tid) {
;     ...
;       for (int sub = 0; sub < 2; ++sub) {
;         const int t = 2 * st + sub;
;         const LAS unsigned char* sb = lds + (st & 1) * AT_SLOT + sub * AT_SUB;
;         const LAS unsigned char* kb = sb + hi * 1024 + r32 * 16;
;         const LAS unsigned char* vb = sb + AT_V + vlane;
;         bf16x8 vf[2][4];
; #pragma unroll
;         for (int dh = 0; dh < 2; ++dh)
; #pragma unroll
;             for (int k = 0; k < 4; ++k) { const s16x4 lo = vtr(vb + dh * 4096 + k * 1024), hh = vtr(vb + dh * 4096 + k * 1024 + 512);
;                 vf[dh][k] = (bf16x8){lo[0], lo[1], lo[2], lo[3], hh[0], hh[1], hh[2], hh[3]}; }
;         bf16x8 kf[NQ][2];
; #pragma unroll
;         for (int d0 = 0; d0 < NQ; ++d0) { kf[d0][0] = *(const LAS bf16x8*)(kb + d0 * 2048); kf[d0][1] = *(const LAS bf16x8*)(kb + d0 * 2048 + 512); }
;         {
;             if (DIFF) {
; #pragma unroll
;                 for (int r = 0; r < 16; ++r) negm1[r] = -mref1;
;             }
;             f32x16 s0 = negm1, s1 = negm1;
; #pragma unroll
;             for (int d0 = 0; d0 < NQ; ++d0) {
;                 s0 = __builtin_amdgcn_mfma_f32_32x32x16_bf16(kf[d0][0], qf[d0], s0, 0, 0, 0);
;                 s1 = __builtin_amdgcn_mfma_f32_32x32x16_bf16(kf[d0][1], qf[d0], s1, 0, 0, 0);
;             }
;             softmax_pv(s0, s1, mref1, negm1, l1, o1, scr, vf, t == 0, r32, hi);
.LBB0_495:
	s_bitcmp1_b32 s34, 0
	s_cselect_b32 s18, 0xa000, 0
	v_add_u32_e32 v187, s18, v181
	v_add_u32_e32 v163, s18, v184
	ds_read_b128 v[234:237], v187
	ds_read_b128 v[238:241], v187 offset:512
	ds_read_b128 v[242:245], v187 offset:2048
	ds_read_b128 v[188:191], v187 offset:2560
	s_waitcnt lgkmcnt(0)
	v_mfma_f32_32x32x16_bf16 v[80:95], v[234:237], v[104:107], v[194:209]
	v_mfma_f32_32x32x16_bf16 v[80:95], v[242:245], v[112:115], v[80:95]
	v_mfma_f32_32x32x16_bf16 v[64:79], v[238:241], v[104:107], v[194:209]
	v_mfma_f32_32x32x16_bf16 v[64:79], v[188:191], v[112:115], v[64:79]
	ds_read_b64_tr_b16 v[128:129], v163 offset:12288
	ds_read_b64_tr_b16 v[130:131], v163 offset:12800
	ds_read_b64_tr_b16 v[144:145], v163 offset:16384
	ds_read_b64_tr_b16 v[146:147], v163 offset:16896
	ds_read_b64_tr_b16 v[132:133], v163 offset:13312
	ds_read_b64_tr_b16 v[134:135], v163 offset:13824
	ds_read_b64_tr_b16 v[148:149], v163 offset:17408
	ds_read_b64_tr_b16 v[150:151], v163 offset:17920
	ds_read_b128 v[234:237], v187 offset:4096
	ds_read_b128 v[238:241], v187 offset:4608
	ds_read_b128 v[242:245], v187 offset:6144
	ds_read_b128 v[188:191], v187 offset:6656
	s_waitcnt lgkmcnt(7)
	ds_read_b64_tr_b16 v[136:137], v163 offset:14336
	ds_read_b64_tr_b16 v[138:139], v163 offset:14848
	ds_read_b64_tr_b16 v[152:153], v163 offset:18432
	ds_read_b64_tr_b16 v[154:155], v163 offset:18944
	ds_read_b64_tr_b16 v[140:141], v163 offset:15360
	ds_read_b64_tr_b16 v[142:143], v163 offset:15872
	ds_read_b64_tr_b16 v[156:157], v163 offset:19456
	ds_read_b64_tr_b16 v[158:159], v163 offset:19968
	s_cmp_eq_u32 s34, 0
	s_cbranch_scc1 .Ldr_first_00
.Ldr_cont_00:
	v_exp_f32_e32 v80, v80
	v_exp_f32_e32 v81, v81
	v_exp_f32_e32 v82, v82
	v_exp_f32_e32 v83, v83
	v_exp_f32_e32 v84, v84
	v_exp_f32_e32 v85, v85
	v_exp_f32_e32 v86, v86
	v_exp_f32_e32 v87, v87
	v_cvt_pk_bf16_f32 v210, v80, v81
	v_cvt_pk_bf16_f32 v211, v82, v83
	v_cvt_pk_bf16_f32 v212, v84, v85
	v_cvt_pk_bf16_f32 v213, v86, v87
	v_mfma_f32_4x4x4_16b_bf16 v[164:167], v[210:211], v[214:215], v[164:167]
	s_nop 1
	v_mfma_f32_4x4x4_16b_bf16 v[164:167], v[212:213], v[214:215], v[164:167]
	v_mfma_f32_32x32x16_bf16 v[32:47], v[210:213], v[128:131], v[32:47]
	v_mfma_f32_32x32x16_bf16 v[48:63], v[210:213], v[144:147], v[48:63]
	v_exp_f32_e32 v88, v88
	v_exp_f32_e32 v89, v89
	v_exp_f32_e32 v90, v90
	v_exp_f32_e32 v91, v91
	v_exp_f32_e32 v92, v92
	v_exp_f32_e32 v93, v93
	v_exp_f32_e32 v94, v94
	v_exp_f32_e32 v95, v95
	v_cvt_pk_bf16_f32 v248, v88, v89
	v_cvt_pk_bf16_f32 v249, v90, v91
	v_cvt_pk_bf16_f32 v250, v92, v93
	v_cvt_pk_bf16_f32 v251, v94, v95
	v_mfma_f32_4x4x4_16b_bf16 v[164:167], v[248:249], v[214:215], v[164:167]
	s_nop 1
	v_mfma_f32_4x4x4_16b_bf16 v[164:167], v[250:251], v[214:215], v[164:167]
	s_waitcnt lgkmcnt(12)
	v_mfma_f32_32x32x16_bf16 v[32:47], v[248:251], v[132:135], v[32:47]
	v_mfma_f32_32x32x16_bf16 v[48:63], v[248:251], v[148:151], v[48:63]
	s_waitcnt lgkmcnt(8)
	v_mfma_f32_32x32x16_bf16 v[80:95], v[234:237], v[120:123], v[218:233]
	v_mfma_f32_32x32x16_bf16 v[80:95], v[242:245], v[124:127], v[80:95]
	v_exp_f32_e32 v64, v64
	v_exp_f32_e32 v65, v65
	v_exp_f32_e32 v66, v66
	v_exp_f32_e32 v67, v67
	v_exp_f32_e32 v68, v68
	v_exp_f32_e32 v69, v69
	v_exp_f32_e32 v70, v70
	v_exp_f32_e32 v71, v71
	v_cvt_pk_bf16_f32 v210, v64, v65
	v_cvt_pk_bf16_f32 v211, v66, v67
	v_cvt_pk_bf16_f32 v212, v68, v69
	v_cvt_pk_bf16_f32 v213, v70, v71
	v_mfma_f32_4x4x4_16b_bf16 v[164:167], v[210:211], v[214:215], v[164:167]
	s_nop 1
	v_mfma_f32_4x4x4_16b_bf16 v[164:167], v[212:213], v[214:215], v[164:167]
	s_waitcnt lgkmcnt(4)
	v_mfma_f32_32x32x16_bf16 v[32:47], v[210:213], v[136:139], v[32:47]
	v_mfma_f32_32x32x16_bf16 v[48:63], v[210:213], v[152:155], v[48:63]
	v_exp_f32_e32 v72, v72
	v_exp_f32_e32 v73, v73
	v_exp_f32_e32 v74, v74
	v_exp_f32_e32 v75, v75
	v_exp_f32_e32 v76, v76
	v_exp_f32_e32 v77, v77
	v_exp_f32_e32 v78, v78
	v_exp_f32_e32 v79, v79
	v_cvt_pk_bf16_f32 v248, v72, v73
	v_cvt_pk_bf16_f32 v249, v74, v75
	v_cvt_pk_bf16_f32 v250, v76, v77
	v_cvt_pk_bf16_f32 v251, v78, v79
	v_mfma_f32_4x4x4_16b_bf16 v[164:167], v[248:249], v[214:215], v[164:167]
	s_nop 1
	v_mfma_f32_4x4x4_16b_bf16 v[164:167], v[250:251], v[214:215], v[164:167]
	v_mfma_f32_32x32x16_bf16 v[64:79], v[238:241], v[120:123], v[218:233]
	v_mfma_f32_32x32x16_bf16 v[64:79], v[188:191], v[124:127], v[64:79]
	s_waitcnt lgkmcnt(0)
	v_mfma_f32_32x32x16_bf16 v[32:47], v[248:251], v[140:143], v[32:47]
	v_mfma_f32_32x32x16_bf16 v[48:63], v[248:251], v[156:159], v[48:63]
	ds_read_b128 v[234:237], v187 offset:20480
	ds_read_b128 v[238:241], v187 offset:20992
	ds_read_b128 v[242:245], v187 offset:22528
	ds_read_b128 v[188:191], v187 offset:23040
	s_cmp_eq_u32 s34, 0
	s_cbranch_scc1 .Ldr_first_01
; #define LAS __attribute__((address_space(3)))
; __device__ __forceinline__ unsigned cvt_pk_bf16(float lo, float hi) { const f32x2 v = {lo, hi}; const bf16x2_t b = __builtin_convertvector(v, bf16x2_t); return __builtin_bit_cast(unsigned, b); }
; __device__ __forceinline__ void softmax_pv(f32x16& s0, f32x16& s1, float& mref, f32x16& negm, float& lsum, f32x16 (&o)[2], LAS float* fac, const bf16x8 (&vf)[2][4], bool first, int r32, int hi) {
;     ...
;     float ps0 = 0.f, ps1 = 0.f;
; #pragma unroll
;     for (int r = 0; r < 16; ++r) { s0[r] = __builtin_amdgcn_exp2f(s0[r]); s1[r] = __builtin_amdgcn_exp2f(s1[r]); ps0 += s0[r]; ps1 += s1[r]; }
;     lsum += ps0 + ps1;
;     bf16x8 pa[4];
; #pragma unroll
;     for (int k = 0; k < 4; ++k) {
;         const f32x16& s = (k < 2) ? s0 : s1; const int rb = 8 * (k & 1);
;         u32x4 w; w.x = cvt_pk_bf16(s[rb + 0], s[rb + 1]); w.y = cvt_pk_bf16(s[rb + 2], s[rb + 3]); w.z = cvt_pk_bf16(s[rb + 4], s[rb + 5]); w.w = cvt_pk_bf16(s[rb + 6], s[rb + 7]);
;         pa[k] = __builtin_bit_cast(bf16x8, w);
;     }
; #pragma unroll
;     for (int k = 0; k < 4; ++k) {
;         o[0] = __builtin_amdgcn_mfma_f32_32x32x16_bf16(pa[k], vf[0][k], o[0], 0, 0, 0);
;         o[1] = __builtin_amdgcn_mfma_f32_32x32x16_bf16(pa[k], vf[1][k], o[1], 0, 0, 0);
;     }
; template <bool DIFF>
; __device__ __forceinline__ void attn_item(const Params& p, int l, int I, LAS unsigned char* lds, const int tid) {
;     ...
;         if (DIFF) {
; #pragma unroll
;             for (int r = 0; r < 16; ++r) negm2[r] = -mref2;
;             f32x16 s0 = negm2, s1 = negm2;
;             bf16x8 kg[2][2];
; #pragma unroll
;             for (int d0 = 0; d0 < 2; ++d0) { kg[d0][0] = *(const LAS bf16x8*)(kb + 4096 + d0 * 2048); kg[d0][1] = *(const LAS bf16x8*)(kb + 4096 + d0 * 2048 + 512); }
; #pragma unroll
;             for (int d0 = 0; d0 < 2; ++d0) {
;                 s0 = __builtin_amdgcn_mfma_f32_32x32x16_bf16(kg[d0][0], qf[2 + d0], s0, 0, 0, 0);
;                 s1 = __builtin_amdgcn_mfma_f32_32x32x16_bf16(kg[d0][1], qf[2 + d0], s1, 0, 0, 0);
;             }
;             softmax_pv(s0, s1, mref2, negm2, l2, o2, scr + 32, vf, t == 0, r32, hi);
.Ldr_cont_01:
	v_exp_f32_e32 v80, v80
	v_exp_f32_e32 v81, v81
	v_exp_f32_e32 v82, v82
	v_exp_f32_e32 v83, v83
	v_exp_f32_e32 v84, v84
	v_exp_f32_e32 v85, v85
	v_exp_f32_e32 v86, v86
	v_exp_f32_e32 v87, v87
	v_cvt_pk_bf16_f32 v210, v80, v81
	v_cvt_pk_bf16_f32 v211, v82, v83
	v_cvt_pk_bf16_f32 v212, v84, v85
	v_cvt_pk_bf16_f32 v213, v86, v87
	v_mfma_f32_4x4x4_16b_bf16 v[172:175], v[210:211], v[214:215], v[172:175]
	s_nop 1
	v_mfma_f32_4x4x4_16b_bf16 v[172:175], v[212:213], v[214:215], v[172:175]
	v_mfma_f32_32x32x16_bf16 v[0:15], v[210:213], v[128:131], v[0:15]
	v_mfma_f32_32x32x16_bf16 v[16:31], v[210:213], v[144:147], v[16:31]
	v_exp_f32_e32 v88, v88
	v_exp_f32_e32 v89, v89
	v_exp_f32_e32 v90, v90
	v_exp_f32_e32 v91, v91
	v_exp_f32_e32 v92, v92
	v_exp_f32_e32 v93, v93
	v_exp_f32_e32 v94, v94
	v_exp_f32_e32 v95, v95
	v_cvt_pk_bf16_f32 v248, v88, v89
	v_cvt_pk_bf16_f32 v249, v90, v91
	v_cvt_pk_bf16_f32 v250, v92, v93
	v_cvt_pk_bf16_f32 v251, v94, v95
	v_mfma_f32_4x4x4_16b_bf16 v[172:175], v[248:249], v[214:215], v[172:175]
	s_nop 1
	v_mfma_f32_4x4x4_16b_bf16 v[172:175], v[250:251], v[214:215], v[172:175]
	v_mfma_f32_32x32x16_bf16 v[0:15], v[248:251], v[132:135], v[0:15]
	v_mfma_f32_32x32x16_bf16 v[16:31], v[248:251], v[148:151], v[16:31]
	s_waitcnt lgkmcnt(0)
	v_mfma_f32_32x32x16_bf16 v[80:95], v[234:237], v[104:107], v[194:209]
	v_mfma_f32_32x32x16_bf16 v[80:95], v[242:245], v[112:115], v[80:95]
	v_exp_f32_e32 v64, v64
	v_exp_f32_e32 v65, v65
	v_exp_f32_e32 v66, v66
	v_exp_f32_e32 v67, v67
	v_exp_f32_e32 v68, v68
	v_exp_f32_e32 v69, v69
	v_exp_f32_e32 v70, v70
	v_exp_f32_e32 v71, v71
	v_cvt_pk_bf16_f32 v210, v64, v65
	v_cvt_pk_bf16_f32 v211, v66, v67
	v_cvt_pk_bf16_f32 v212, v68, v69
	v_cvt_pk_bf16_f32 v213, v70, v71
	v_mfma_f32_4x4x4_16b_bf16 v[172:175], v[210:211], v[214:215], v[172:175]
	s_nop 1
	v_mfma_f32_4x4x4_16b_bf16 v[172:175], v[212:213], v[214:215], v[172:175]
	v_mfma_f32_32x32x16_bf16 v[0:15], v[210:213], v[136:139], v[0:15]
	v_mfma_f32_32x32x16_bf16 v[16:31], v[210:213], v[152:155], v[16:31]
	v_exp_f32_e32 v72, v72
	v_exp_f32_e32 v73, v73
	v_exp_f32_e32 v74, v74
	v_exp_f32_e32 v75, v75
	v_exp_f32_e32 v76, v76
	v_exp_f32_e32 v77, v77
	v_exp_f32_e32 v78, v78
	v_exp_f32_e32 v79, v79
	v_cvt_pk_bf16_f32 v248, v72, v73
	v_cvt_pk_bf16_f32 v249, v74, v75
	v_cvt_pk_bf16_f32 v250, v76, v77
	v_cvt_pk_bf16_f32 v251, v78, v79
	v_mfma_f32_4x4x4_16b_bf16 v[172:175], v[248:249], v[214:215], v[172:175]
	s_nop 1
	v_mfma_f32_4x4x4_16b_bf16 v[172:175], v[250:251], v[214:215], v[172:175]
	v_mfma_f32_32x32x16_bf16 v[64:79], v[238:241], v[104:107], v[194:209]
	v_mfma_f32_32x32x16_bf16 v[64:79], v[188:191], v[112:115], v[64:79]
	v_mfma_f32_32x32x16_bf16 v[0:15], v[248:251], v[140:143], v[0:15]
	v_mfma_f32_32x32x16_bf16 v[16:31], v[248:251], v[156:159], v[16:31]
	ds_read_b128 v[234:237], v187 offset:24576
	ds_read_b128 v[238:241], v187 offset:25088
	ds_read_b128 v[242:245], v187 offset:26624
	ds_read_b128 v[188:191], v187 offset:27136
	ds_read_b64_tr_b16 v[128:129], v163 offset:32768
	ds_read_b64_tr_b16 v[130:131], v163 offset:33280
	ds_read_b64_tr_b16 v[144:145], v163 offset:36864
	ds_read_b64_tr_b16 v[146:147], v163 offset:37376
	ds_read_b64_tr_b16 v[132:133], v163 offset:33792
	ds_read_b64_tr_b16 v[134:135], v163 offset:34304
	ds_read_b64_tr_b16 v[148:149], v163 offset:37888
	ds_read_b64_tr_b16 v[150:151], v163 offset:38400
	s_waitcnt lgkmcnt(7)
	ds_read_b64_tr_b16 v[136:137], v163 offset:34816
	ds_read_b64_tr_b16 v[138:139], v163 offset:35328
	ds_read_b64_tr_b16 v[152:153], v163 offset:38912
	ds_read_b64_tr_b16 v[154:155], v163 offset:39424
	ds_read_b64_tr_b16 v[140:141], v163 offset:35840
	ds_read_b64_tr_b16 v[142:143], v163 offset:36352
	ds_read_b64_tr_b16 v[156:157], v163 offset:39936
	ds_read_b64_tr_b16 v[158:159], v163 offset:40448
	v_exp_f32_e32 v80, v80
	v_exp_f32_e32 v81, v81
	v_exp_f32_e32 v82, v82
	v_exp_f32_e32 v83, v83
	v_exp_f32_e32 v84, v84
	v_exp_f32_e32 v85, v85
	v_exp_f32_e32 v86, v86
	v_exp_f32_e32 v87, v87
	v_cvt_pk_bf16_f32 v210, v80, v81
	v_cvt_pk_bf16_f32 v211, v82, v83
	v_cvt_pk_bf16_f32 v212, v84, v85
	v_cvt_pk_bf16_f32 v213, v86, v87
	v_mfma_f32_4x4x4_16b_bf16 v[164:167], v[210:211], v[214:215], v[164:167]
	s_nop 1
	v_mfma_f32_4x4x4_16b_bf16 v[164:167], v[212:213], v[214:215], v[164:167]
	s_waitcnt lgkmcnt(12)
	v_mfma_f32_32x32x16_bf16 v[32:47], v[210:213], v[128:131], v[32:47]
	v_mfma_f32_32x32x16_bf16 v[48:63], v[210:213], v[144:147], v[48:63]
	v_exp_f32_e32 v88, v88
	v_exp_f32_e32 v89, v89
	v_exp_f32_e32 v90, v90
	v_exp_f32_e32 v91, v91
	v_exp_f32_e32 v92, v92
	v_exp_f32_e32 v93, v93
	v_exp_f32_e32 v94, v94
	v_exp_f32_e32 v95, v95
	v_cvt_pk_bf16_f32 v248, v88, v89
	v_cvt_pk_bf16_f32 v249, v90, v91
	v_cvt_pk_bf16_f32 v250, v92, v93
	v_cvt_pk_bf16_f32 v251, v94, v95
	v_mfma_f32_4x4x4_16b_bf16 v[164:167], v[248:249], v[214:215], v[164:167]
	s_nop 1
	v_mfma_f32_4x4x4_16b_bf16 v[164:167], v[250:251], v[214:215], v[164:167]
	s_waitcnt lgkmcnt(8)
	v_mfma_f32_32x32x16_bf16 v[32:47], v[248:251], v[132:135], v[32:47]
	v_mfma_f32_32x32x16_bf16 v[48:63], v[248:251], v[148:151], v[48:63]
	v_mfma_f32_32x32x16_bf16 v[80:95], v[234:237], v[120:123], v[218:233]
	v_mfma_f32_32x32x16_bf16 v[80:95], v[242:245], v[124:127], v[80:95]
	v_exp_f32_e32 v64, v64
	v_exp_f32_e32 v65, v65
	v_exp_f32_e32 v66, v66
	v_exp_f32_e32 v67, v67
	v_exp_f32_e32 v68, v68
	v_exp_f32_e32 v69, v69
	v_exp_f32_e32 v70, v70
	v_exp_f32_e32 v71, v71
	v_cvt_pk_bf16_f32 v210, v64, v65
	v_cvt_pk_bf16_f32 v211, v66, v67
	v_cvt_pk_bf16_f32 v212, v68, v69
	v_cvt_pk_bf16_f32 v213, v70, v71
	v_mfma_f32_4x4x4_16b_bf16 v[164:167], v[210:211], v[214:215], v[164:167]
	s_nop 1
	v_mfma_f32_4x4x4_16b_bf16 v[164:167], v[212:213], v[214:215], v[164:167]
	s_waitcnt lgkmcnt(4)
; __device__ __forceinline__ unsigned cvt_pk_bf16(float lo, float hi) { const f32x2 v = {lo, hi}; const bf16x2_t b = __builtin_convertvector(v, bf16x2_t); return __builtin_bit_cast(unsigned, b); }
; __device__ __forceinline__ int crow(int r, int hi) { return (r & 3) + 8 * (r >> 2) + 4 * hi; }
; __device__ __forceinline__ void softmax_pv(f32x16& s0, f32x16& s1, float& mref, f32x16& negm, float& lsum, f32x16 (&o)[2], LAS float* fac, const bf16x8 (&vf)[2][4], bool first, int r32, int hi) {
;     ...
;     if (__builtin_expect(first || __any(mx > 16.0f), 0)) {
;         const float d = first ? mx : fmaxf(mx, 0.f);
;         const float f = __builtin_amdgcn_exp2f(-d);
;         lsum *= f; mref += d;
; #pragma unroll
;         for (int r = 0; r < 16; ++r) { s0[r] -= d; s1[r] -= d; negm[r] = -mref; }
;         if (hi == 0) fac[r32] = f;
;         asm volatile("s_waitcnt lgkmcnt(0)" ::: "memory");
; #pragma unroll
;         for (int r = 0; r < 16; ++r) { const float ff = fac[crow(r, hi)]; o[0][r] *= ff; o[1][r] *= ff; }
;     }
;     float ps0 = 0.f, ps1 = 0.f;
; #pragma unroll
;     for (int r = 0; r < 16; ++r) { s0[r] = __builtin_amdgcn_exp2f(s0[r]); s1[r] = __builtin_amdgcn_exp2f(s1[r]); ps0 += s0[r]; ps1 += s1[r]; }
;     lsum += ps0 + ps1;
;     bf16x8 pa[4];
; #pragma unroll
;     for (int k = 0; k < 4; ++k) {
;         const f32x16& s = (k < 2) ? s0 : s1; const int rb = 8 * (k & 1);
;         u32x4 w; w.x = cvt_pk_bf16(s[rb + 0], s[rb + 1]); w.y = cvt_pk_bf16(s[rb + 2], s[rb + 3]); w.z = cvt_pk_bf16(s[rb + 4], s[rb + 5]); w.w = cvt_pk_bf16(s[rb + 6], s[rb + 7]);
;         pa[k] = __builtin_bit_cast(bf16x8, w);
;     }
; #pragma unroll
;     for (int k = 0; k < 4; ++k) {
;         o[0] = __builtin_amdgcn_mfma_f32_32x32x16_bf16(pa[k], vf[0][k], o[0], 0, 0, 0);
;         o[1] = __builtin_amdgcn_mfma_f32_32x32x16_bf16(pa[k], vf[1][k], o[1], 0, 0, 0);
;     }
; template <bool DIFF>
; __device__ __forceinline__ void attn_item(const Params& p, int l, int I, LAS unsigned char* lds, const int tid) {
;     ...
;       }
;         if (more) { lwrite((st + 1) & 1, 0); lwrite((st + 1) & 1, 1); }
;         __syncthreads();
	v_mfma_f32_32x32x16_bf16 v[32:47], v[210:213], v[136:139], v[32:47]
	v_mfma_f32_32x32x16_bf16 v[48:63], v[210:213], v[152:155], v[48:63]
	v_exp_f32_e32 v72, v72
	v_exp_f32_e32 v73, v73
	v_exp_f32_e32 v74, v74
	v_exp_f32_e32 v75, v75
	v_exp_f32_e32 v76, v76
	v_exp_f32_e32 v77, v77
	v_exp_f32_e32 v78, v78
	v_exp_f32_e32 v79, v79
	v_cvt_pk_bf16_f32 v248, v72, v73
	v_cvt_pk_bf16_f32 v249, v74, v75
	v_cvt_pk_bf16_f32 v250, v76, v77
	v_cvt_pk_bf16_f32 v251, v78, v79
	v_mfma_f32_4x4x4_16b_bf16 v[164:167], v[248:249], v[214:215], v[164:167]
	s_nop 1
	v_mfma_f32_4x4x4_16b_bf16 v[164:167], v[250:251], v[214:215], v[164:167]
	v_mfma_f32_32x32x16_bf16 v[64:79], v[238:241], v[120:123], v[218:233]
	v_mfma_f32_32x32x16_bf16 v[64:79], v[188:191], v[124:127], v[64:79]
	s_waitcnt lgkmcnt(0)
	v_mfma_f32_32x32x16_bf16 v[32:47], v[248:251], v[140:143], v[32:47]
	v_mfma_f32_32x32x16_bf16 v[48:63], v[248:251], v[156:159], v[48:63]
	v_exp_f32_e32 v80, v80
	v_exp_f32_e32 v81, v81
	v_exp_f32_e32 v82, v82
	v_exp_f32_e32 v83, v83
	v_exp_f32_e32 v84, v84
	v_exp_f32_e32 v85, v85
	v_exp_f32_e32 v86, v86
	v_exp_f32_e32 v87, v87
	v_cvt_pk_bf16_f32 v210, v80, v81
	v_cvt_pk_bf16_f32 v211, v82, v83
	v_cvt_pk_bf16_f32 v212, v84, v85
	v_cvt_pk_bf16_f32 v213, v86, v87
	v_mfma_f32_4x4x4_16b_bf16 v[172:175], v[210:211], v[214:215], v[172:175]
	s_nop 1
	v_mfma_f32_4x4x4_16b_bf16 v[172:175], v[212:213], v[214:215], v[172:175]
	v_mfma_f32_32x32x16_bf16 v[0:15], v[210:213], v[128:131], v[0:15]
	v_mfma_f32_32x32x16_bf16 v[16:31], v[210:213], v[144:147], v[16:31]
	v_exp_f32_e32 v88, v88
	v_exp_f32_e32 v89, v89
	v_exp_f32_e32 v90, v90
	v_exp_f32_e32 v91, v91
	v_exp_f32_e32 v92, v92
	v_exp_f32_e32 v93, v93
	v_exp_f32_e32 v94, v94
	v_exp_f32_e32 v95, v95
	v_cvt_pk_bf16_f32 v248, v88, v89
	v_cvt_pk_bf16_f32 v249, v90, v91
	v_cvt_pk_bf16_f32 v250, v92, v93
	v_cvt_pk_bf16_f32 v251, v94, v95
	v_mfma_f32_4x4x4_16b_bf16 v[172:175], v[248:249], v[214:215], v[172:175]
	s_nop 1
	v_mfma_f32_4x4x4_16b_bf16 v[172:175], v[250:251], v[214:215], v[172:175]
	v_mfma_f32_32x32x16_bf16 v[0:15], v[248:251], v[132:135], v[0:15]
	v_mfma_f32_32x32x16_bf16 v[16:31], v[248:251], v[148:151], v[16:31]
	v_exp_f32_e32 v64, v64
	v_exp_f32_e32 v65, v65
	v_exp_f32_e32 v66, v66
	v_exp_f32_e32 v67, v67
	v_exp_f32_e32 v68, v68
	v_exp_f32_e32 v69, v69
	v_exp_f32_e32 v70, v70
	v_exp_f32_e32 v71, v71
	v_cvt_pk_bf16_f32 v210, v64, v65
	v_cvt_pk_bf16_f32 v211, v66, v67
	v_cvt_pk_bf16_f32 v212, v68, v69
	v_cvt_pk_bf16_f32 v213, v70, v71
	v_mfma_f32_4x4x4_16b_bf16 v[172:175], v[210:211], v[214:215], v[172:175]
	s_nop 1
	v_mfma_f32_4x4x4_16b_bf16 v[172:175], v[212:213], v[214:215], v[172:175]
	v_mfma_f32_32x32x16_bf16 v[0:15], v[210:213], v[136:139], v[0:15]
	v_mfma_f32_32x32x16_bf16 v[16:31], v[210:213], v[152:155], v[16:31]
	v_exp_f32_e32 v72, v72
	v_exp_f32_e32 v73, v73
	v_exp_f32_e32 v74, v74
	v_exp_f32_e32 v75, v75
	v_exp_f32_e32 v76, v76
	v_exp_f32_e32 v77, v77
	v_exp_f32_e32 v78, v78
	v_exp_f32_e32 v79, v79
	v_cvt_pk_bf16_f32 v248, v72, v73
	v_cvt_pk_bf16_f32 v249, v74, v75
	v_cvt_pk_bf16_f32 v250, v76, v77
	v_cvt_pk_bf16_f32 v251, v78, v79
	v_mfma_f32_4x4x4_16b_bf16 v[172:175], v[248:249], v[214:215], v[172:175]
	s_nop 1
	v_mfma_f32_4x4x4_16b_bf16 v[172:175], v[250:251], v[214:215], v[172:175]
	v_mfma_f32_32x32x16_bf16 v[0:15], v[248:251], v[140:143], v[0:15]
	v_mfma_f32_32x32x16_bf16 v[16:31], v[248:251], v[156:159], v[16:31]
	s_nop 5
	v_max3_f32 v210, v164, v165, v166
	v_max3_f32 v210, v210, v167, v172
	v_max3_f32 v210, v210, v173, v174
	v_max_f32_e32 v210, v210, v175
	v_cmp_lt_f32_e32 vcc, 0x47800000, v210
	s_cbranch_vccnz .Ldq
.Ldqc:
	s_andn2_b64 vcc, exec, s[8:9]
	s_cbranch_vccnz .LBB0_492
	s_andn2_b32 s8, 1, s34
	s_mul_i32 s8, s8, 0xa000
	s_add_i32 s8, s8, 0
	v_add_u32_e32 v128, s8, v178
	v_add_u32_e32 v129, s8, v179
	s_waitcnt vmcnt(3)
	ds_write_b128 v128, v[96:99]
	s_waitcnt vmcnt(2)
	ds_write_b128 v129, v[100:103] offset:12288
	s_waitcnt vmcnt(1)
	ds_write_b128 v128, v[108:111] offset:20480
	s_waitcnt vmcnt(0)
	ds_write_b128 v129, v[116:119] offset:32768
	s_branch .LBB0_492
.Ldr_first_00:
	s_nop 7
	s_nop 3
	v_max3_f32 v210, v80, v81, v82
	v_max3_f32 v211, v64, v65, v66
	v_max3_f32 v210, v210, v83, v84
	v_max3_f32 v211, v211, v67, v68
	v_max3_f32 v210, v210, v85, v86
	v_max3_f32 v211, v211, v69, v70
	v_max3_f32 v210, v210, v87, v88
	v_max3_f32 v211, v211, v71, v72
	v_max3_f32 v210, v210, v89, v90
	v_max3_f32 v211, v211, v73, v74
	v_max3_f32 v210, v210, v91, v92
	v_max3_f32 v211, v211, v75, v76
	v_max3_f32 v210, v210, v93, v94
	v_max3_f32 v211, v211, v77, v78
	v_max_f32_e32 v212, v95, v79
	v_max3_f32 v210, v210, v211, v212
	v_mov_b32_e32 v211, v210
	s_nop 1
	v_permlane32_swap_b32_e32 v210, v211
	v_max_f32_e32 v160, v210, v211
	v_exp_f32_e64 v246, -v160
	v_sub_f32_e32 v80, v80, v160
	v_sub_f32_e32 v64, v64, v160
	v_sub_f32_e32 v81, v81, v160
	v_sub_f32_e32 v65, v65, v160
	v_sub_f32_e32 v82, v82, v160
	v_sub_f32_e32 v66, v66, v160
	v_sub_f32_e32 v83, v83, v160
	v_sub_f32_e32 v67, v67, v160
	v_sub_f32_e32 v84, v84, v160
	v_sub_f32_e32 v68, v68, v160
	v_sub_f32_e32 v85, v85, v160
	v_sub_f32_e32 v69, v69, v160
	v_sub_f32_e32 v86, v86, v160
	v_sub_f32_e32 v70, v70, v160
	v_sub_f32_e32 v87, v87, v160
	v_sub_f32_e32 v71, v71, v160
	v_sub_f32_e32 v88, v88, v160
	v_sub_f32_e32 v72, v72, v160
	v_sub_f32_e32 v89, v89, v160
	v_sub_f32_e32 v73, v73, v160
	v_sub_f32_e32 v90, v90, v160
	v_sub_f32_e32 v74, v74, v160
	v_sub_f32_e32 v91, v91, v160
	v_sub_f32_e32 v75, v75, v160
	v_sub_f32_e32 v92, v92, v160
	v_sub_f32_e32 v76, v76, v160
	v_sub_f32_e32 v93, v93, v160
	v_sub_f32_e32 v77, v77, v160
	v_sub_f32_e32 v94, v94, v160
	v_sub_f32_e32 v78, v78, v160
	v_sub_f32_e32 v95, v95, v160
	v_sub_f32_e32 v79, v79, v160
	s_and_saveexec_b64 s[20:21], s[4:5]
	ds_write_b32 v180, v246
	s_or_b64 exec, exec, s[20:21]
	v_add_f32_e32 v186, v186, v160
	v_xor_b32_e32 v194, 0x80000000, v186
	v_mov_b32_e32 v195, v194
	v_mov_b32_e32 v196, v194
	v_mov_b32_e32 v197, v194
	v_mov_b32_e32 v198, v194
	v_mov_b32_e32 v199, v194
	v_mov_b32_e32 v200, v194
	v_mov_b32_e32 v201, v194
	v_mov_b32_e32 v202, v194
	v_mov_b32_e32 v203, v194
	v_mov_b32_e32 v204, v194
	v_mov_b32_e32 v205, v194
	v_mov_b32_e32 v206, v194
	v_mov_b32_e32 v207, v194
	v_mov_b32_e32 v208, v194
	v_mov_b32_e32 v209, v194
	s_waitcnt lgkmcnt(0)
; __device__ __forceinline__ int crow(int r, int hi) { return (r & 3) + 8 * (r >> 2) + 4 * hi; }
; __device__ __forceinline__ void softmax_pv(f32x16& s0, f32x16& s1, float& mref, f32x16& negm, float& lsum, f32x16 (&o)[2], LAS float* fac, const bf16x8 (&vf)[2][4], bool first, int r32, int hi) {
;     ...
;     if (__builtin_expect(first || __any(mx > 16.0f), 0)) {
;         const float d = first ? mx : fmaxf(mx, 0.f);
;         const float f = __builtin_amdgcn_exp2f(-d);
;         lsum *= f; mref += d;
; #pragma unroll
;         for (int r = 0; r < 16; ++r) { s0[r] -= d; s1[r] -= d; negm[r] = -mref; }
;         if (hi == 0) fac[r32] = f;
;         asm volatile("s_waitcnt lgkmcnt(0)" ::: "memory");
; #pragma unroll
;         for (int r = 0; r < 16; ++r) { const float ff = fac[crow(r, hi)]; o[0][r] *= ff; o[1][r] *= ff; }
;     }
	v_add_u32_e32 v160, s35, v192
	ds_read_b128 v[210:213], v160
	ds_read_b128 v[248:251], v160 offset:32
	s_waitcnt lgkmcnt(0)
	v_pk_mul_f32 v[32:33], v[32:33], v[210:211]
	v_pk_mul_f32 v[34:35], v[34:35], v[212:213]
	v_pk_mul_f32 v[36:37], v[36:37], v[248:249]
	v_pk_mul_f32 v[38:39], v[38:39], v[250:251]
	v_pk_mul_f32 v[48:49], v[48:49], v[210:211]
	v_pk_mul_f32 v[50:51], v[50:51], v[212:213]
	v_pk_mul_f32 v[52:53], v[52:53], v[248:249]
	v_pk_mul_f32 v[54:55], v[54:55], v[250:251]
	ds_read_b128 v[210:213], v160 offset:64
	ds_read_b128 v[248:251], v160 offset:96
	s_waitcnt lgkmcnt(0)
	v_pk_mul_f32 v[40:41], v[40:41], v[210:211]
	v_pk_mul_f32 v[42:43], v[42:43], v[212:213]
	v_pk_mul_f32 v[44:45], v[44:45], v[248:249]
	v_pk_mul_f32 v[46:47], v[46:47], v[250:251]
	v_pk_mul_f32 v[56:57], v[56:57], v[210:211]
	v_pk_mul_f32 v[58:59], v[58:59], v[212:213]
	v_pk_mul_f32 v[60:61], v[60:61], v[248:249]
	v_pk_mul_f32 v[62:63], v[62:63], v[250:251]
	s_branch .Ldr_cont_00
.Ldr_first_01:
	s_nop 7
	s_nop 3
	v_max3_f32 v210, v80, v81, v82
	v_max3_f32 v211, v64, v65, v66
	v_max3_f32 v210, v210, v83, v84
	v_max3_f32 v211, v211, v67, v68
	v_max3_f32 v210, v210, v85, v86
	v_max3_f32 v211, v211, v69, v70
	v_max3_f32 v210, v210, v87, v88
	v_max3_f32 v211, v211, v71, v72
	v_max3_f32 v210, v210, v89, v90
	v_max3_f32 v211, v211, v73, v74
	v_max3_f32 v210, v210, v91, v92
	v_max3_f32 v211, v211, v75, v76
	v_max3_f32 v210, v210, v93, v94
	v_max3_f32 v211, v211, v77, v78
	v_max_f32_e32 v212, v95, v79
	v_max3_f32 v210, v210, v211, v212
	v_mov_b32_e32 v211, v210
	s_nop 1
	v_permlane32_swap_b32_e32 v210, v211
	v_max_f32_e32 v160, v210, v211
	v_exp_f32_e64 v246, -v160
	v_sub_f32_e32 v80, v80, v160
	v_sub_f32_e32 v64, v64, v160
	v_sub_f32_e32 v81, v81, v160
	v_sub_f32_e32 v65, v65, v160
	v_sub_f32_e32 v82, v82, v160
	v_sub_f32_e32 v66, v66, v160
	v_sub_f32_e32 v83, v83, v160
	v_sub_f32_e32 v67, v67, v160
	v_sub_f32_e32 v84, v84, v160
	v_sub_f32_e32 v68, v68, v160
	v_sub_f32_e32 v85, v85, v160
	v_sub_f32_e32 v69, v69, v160
	v_sub_f32_e32 v86, v86, v160
	v_sub_f32_e32 v70, v70, v160
	v_sub_f32_e32 v87, v87, v160
	v_sub_f32_e32 v71, v71, v160
	v_sub_f32_e32 v88, v88, v160
	v_sub_f32_e32 v72, v72, v160
	v_sub_f32_e32 v89, v89, v160
	v_sub_f32_e32 v73, v73, v160
	v_sub_f32_e32 v90, v90, v160
	v_sub_f32_e32 v74, v74, v160
	v_sub_f32_e32 v91, v91, v160
	v_sub_f32_e32 v75, v75, v160
	v_sub_f32_e32 v92, v92, v160
	v_sub_f32_e32 v76, v76, v160
	v_sub_f32_e32 v93, v93, v160
	v_sub_f32_e32 v77, v77, v160
	v_sub_f32_e32 v94, v94, v160
	v_sub_f32_e32 v78, v78, v160
	v_sub_f32_e32 v95, v95, v160
	v_sub_f32_e32 v79, v79, v160
	s_and_saveexec_b64 s[20:21], s[4:5]
	ds_write_b32 v180, v246 offset:128
	s_or_b64 exec, exec, s[20:21]
	v_add_f32_e32 v185, v185, v160
	v_xor_b32_e32 v218, 0x80000000, v185
	v_mov_b32_e32 v219, v218
	v_mov_b32_e32 v220, v218
	v_mov_b32_e32 v221, v218
	v_mov_b32_e32 v222, v218
	v_mov_b32_e32 v223, v218
	v_mov_b32_e32 v224, v218
	v_mov_b32_e32 v225, v218
	v_mov_b32_e32 v226, v218
	v_mov_b32_e32 v227, v218
	v_mov_b32_e32 v228, v218
	v_mov_b32_e32 v229, v218
	v_mov_b32_e32 v230, v218
	v_mov_b32_e32 v231, v218
	v_mov_b32_e32 v232, v218
	v_mov_b32_e32 v233, v218
	s_waitcnt lgkmcnt(0)
	v_add_u32_e32 v160, s35, v192
	ds_read_b128 v[210:213], v160 offset:128
	ds_read_b128 v[248:251], v160 offset:160
	s_waitcnt lgkmcnt(0)
	v_pk_mul_f32 v[0:1], v[0:1], v[210:211]
	v_pk_mul_f32 v[2:3], v[2:3], v[212:213]
	v_pk_mul_f32 v[4:5], v[4:5], v[248:249]
	v_pk_mul_f32 v[6:7], v[6:7], v[250:251]
	v_pk_mul_f32 v[16:17], v[16:17], v[210:211]
	v_pk_mul_f32 v[18:19], v[18:19], v[212:213]
	v_pk_mul_f32 v[20:21], v[20:21], v[248:249]
	v_pk_mul_f32 v[22:23], v[22:23], v[250:251]
	ds_read_b128 v[210:213], v160 offset:192
	ds_read_b128 v[248:251], v160 offset:224
	s_waitcnt lgkmcnt(0)
	v_pk_mul_f32 v[8:9], v[8:9], v[210:211]
	v_pk_mul_f32 v[10:11], v[10:11], v[212:213]
	v_pk_mul_f32 v[12:13], v[12:13], v[248:249]
	v_pk_mul_f32 v[14:15], v[14:15], v[250:251]
	v_pk_mul_f32 v[24:25], v[24:25], v[210:211]
	v_pk_mul_f32 v[26:27], v[26:27], v[212:213]
	v_pk_mul_f32 v[28:29], v[28:29], v[248:249]
	v_pk_mul_f32 v[30:31], v[30:31], v[250:251]
	s_branch .Ldr_cont_01
; __device__ __forceinline__ int crow(int r, int hi) { return (r & 3) + 8 * (r >> 2) + 4 * hi; }
; __device__ __forceinline__ float half_sum(float m) { auto rr = __builtin_amdgcn_permlane32_swap(__float_as_uint(m), __float_as_uint(m), false, false); return __uint_as_float(rr[0]) + __uint_as_float(rr[1]); }
; __device__ __forceinline__ void softmax_pv(f32x16& s0, f32x16& s1, float& mref, f32x16& negm, float& lsum, f32x16 (&o)[2], LAS float* fac, const bf16x8 (&vf)[2][4], bool first, int r32, int hi) {
;     ...
;     if (__builtin_expect(first || __any(mx > 16.0f), 0)) {
;         const float d = first ? mx : fmaxf(mx, 0.f);
;         const float f = __builtin_amdgcn_exp2f(-d);
;         lsum *= f; mref += d;
; #pragma unroll
;         for (int r = 0; r < 16; ++r) { s0[r] -= d; s1[r] -= d; negm[r] = -mref; }
;         if (hi == 0) fac[r32] = f;
;         asm volatile("s_waitcnt lgkmcnt(0)" ::: "memory");
; #pragma unroll
;         for (int r = 0; r < 16; ++r) { const float ff = fac[crow(r, hi)]; o[0][r] *= ff; o[1][r] *= ff; }
;     }
; template <bool DIFF>
; __device__ __forceinline__ void attn_item(const Params& p, int l, int I, LAS unsigned char* lds, const int tid) {
;     ...
;     l1 = half_sum(l1); if (DIFF) l2 = half_sum(l2);
;     if (hi == 0) { scr[64 + r32] = l1; if (DIFF) scr[96 + r32] = l2; }
.Ldq:
	s_nop 7
	s_mov_b32 s20, 0xaaaaaaaa
	s_mov_b32 s21, 0xaaaaaaaa
	v_cndmask_b32_e64 v210, v164, v165, s[20:21]
	v_cndmask_b32_e64 v211, v166, v167, s[20:21]
	s_mov_b32 s20, 0xcccccccc
	s_mov_b32 s21, 0xcccccccc
	v_cndmask_b32_e64 v210, v210, v211, s[20:21]
	v_mov_b32_e32 v211, v210
	s_nop 1
	v_permlane32_swap_b32_e32 v210, v211
	v_add_f32_e32 v210, v210, v211
	v_log_f32_e32 v160, v210
	s_nop 0
	v_ceil_f32_e32 v160, v160
	v_max_f32_e32 v160, 0, v160
	v_exp_f32_e64 v246, -v160
	s_nop 7
	v_mul_f32_dpp v164, v246, v164 quad_perm:[0,0,0,0] row_mask:0xf bank_mask:0xf
	v_mul_f32_dpp v165, v246, v165 quad_perm:[1,1,1,1] row_mask:0xf bank_mask:0xf
	v_mul_f32_dpp v166, v246, v166 quad_perm:[2,2,2,2] row_mask:0xf bank_mask:0xf
	v_mul_f32_dpp v167, v246, v167 quad_perm:[3,3,3,3] row_mask:0xf bank_mask:0xf
	s_and_saveexec_b64 s[20:21], s[4:5]
	ds_write_b32 v180, v246
	s_or_b64 exec, exec, s[20:21]
	v_add_f32_e32 v186, v186, v160
	v_xor_b32_e32 v194, 0x80000000, v186
	v_mov_b32_e32 v195, v194
	v_mov_b32_e32 v196, v194
	v_mov_b32_e32 v197, v194
	v_mov_b32_e32 v198, v194
	v_mov_b32_e32 v199, v194
	v_mov_b32_e32 v200, v194
	v_mov_b32_e32 v201, v194
	v_mov_b32_e32 v202, v194
	v_mov_b32_e32 v203, v194
	v_mov_b32_e32 v204, v194
	v_mov_b32_e32 v205, v194
	v_mov_b32_e32 v206, v194
	v_mov_b32_e32 v207, v194
	v_mov_b32_e32 v208, v194
	v_mov_b32_e32 v209, v194
	s_waitcnt lgkmcnt(0)
	v_add_u32_e32 v160, s35, v192
	ds_read_b128 v[210:213], v160
	ds_read_b128 v[248:251], v160 offset:32
	s_waitcnt lgkmcnt(0)
	v_pk_mul_f32 v[32:33], v[32:33], v[210:211]
	v_pk_mul_f32 v[34:35], v[34:35], v[212:213]
	v_pk_mul_f32 v[36:37], v[36:37], v[248:249]
	v_pk_mul_f32 v[38:39], v[38:39], v[250:251]
	v_pk_mul_f32 v[48:49], v[48:49], v[210:211]
	v_pk_mul_f32 v[50:51], v[50:51], v[212:213]
	v_pk_mul_f32 v[52:53], v[52:53], v[248:249]
	v_pk_mul_f32 v[54:55], v[54:55], v[250:251]
	ds_read_b128 v[210:213], v160 offset:64
	ds_read_b128 v[248:251], v160 offset:96
	s_waitcnt lgkmcnt(0)
	v_pk_mul_f32 v[40:41], v[40:41], v[210:211]
	v_pk_mul_f32 v[42:43], v[42:43], v[212:213]
	v_pk_mul_f32 v[44:45], v[44:45], v[248:249]
	v_pk_mul_f32 v[46:47], v[46:47], v[250:251]
	v_pk_mul_f32 v[56:57], v[56:57], v[210:211]
	v_pk_mul_f32 v[58:59], v[58:59], v[212:213]
	v_pk_mul_f32 v[60:61], v[60:61], v[248:249]
	v_pk_mul_f32 v[62:63], v[62:63], v[250:251]
	s_mov_b32 s20, 0xaaaaaaaa
	s_mov_b32 s21, 0xaaaaaaaa
	v_cndmask_b32_e64 v210, v172, v173, s[20:21]
	v_cndmask_b32_e64 v211, v174, v175, s[20:21]
	s_mov_b32 s20, 0xcccccccc
	s_mov_b32 s21, 0xcccccccc
	v_cndmask_b32_e64 v210, v210, v211, s[20:21]
	v_mov_b32_e32 v211, v210
	s_nop 1
	v_permlane32_swap_b32_e32 v210, v211
	v_add_f32_e32 v210, v210, v211
	v_log_f32_e32 v160, v210
	s_nop 0
	v_ceil_f32_e32 v160, v160
	v_max_f32_e32 v160, 0, v160
	v_exp_f32_e64 v246, -v160
	s_nop 7
	v_mul_f32_dpp v172, v246, v172 quad_perm:[0,0,0,0] row_mask:0xf bank_mask:0xf
	v_mul_f32_dpp v173, v246, v173 quad_perm:[1,1,1,1] row_mask:0xf bank_mask:0xf
	v_mul_f32_dpp v174, v246, v174 quad_perm:[2,2,2,2] row_mask:0xf bank_mask:0xf
	v_mul_f32_dpp v175, v246, v175 quad_perm:[3,3,3,3] row_mask:0xf bank_mask:0xf
	s_and_saveexec_b64 s[20:21], s[4:5]
	ds_write_b32 v180, v246 offset:128
	s_or_b64 exec, exec, s[20:21]
	v_add_f32_e32 v185, v185, v160
	v_xor_b32_e32 v218, 0x80000000, v185
	v_mov_b32_e32 v219, v218
	v_mov_b32_e32 v220, v218
	v_mov_b32_e32 v221, v218
	v_mov_b32_e32 v222, v218
	v_mov_b32_e32 v223, v218
	v_mov_b32_e32 v224, v218
	v_mov_b32_e32 v225, v218
	v_mov_b32_e32 v226, v218
	v_mov_b32_e32 v227, v218
	v_mov_b32_e32 v228, v218
	v_mov_b32_e32 v229, v218
	v_mov_b32_e32 v230, v218
	v_mov_b32_e32 v231, v218
	v_mov_b32_e32 v232, v218
	v_mov_b32_e32 v233, v218
	s_waitcnt lgkmcnt(0)
	v_add_u32_e32 v160, s35, v192
	ds_read_b128 v[210:213], v160 offset:128
	ds_read_b128 v[248:251], v160 offset:160
	s_waitcnt lgkmcnt(0)
	v_pk_mul_f32 v[0:1], v[0:1], v[210:211]
	v_pk_mul_f32 v[2:3], v[2:3], v[212:213]
	v_pk_mul_f32 v[4:5], v[4:5], v[248:249]
	v_pk_mul_f32 v[6:7], v[6:7], v[250:251]
	v_pk_mul_f32 v[16:17], v[16:17], v[210:211]
	v_pk_mul_f32 v[18:19], v[18:19], v[212:213]
	v_pk_mul_f32 v[20:21], v[20:21], v[248:249]
	v_pk_mul_f32 v[22:23], v[22:23], v[250:251]
	ds_read_b128 v[210:213], v160 offset:192
	ds_read_b128 v[248:251], v160 offset:224
	s_waitcnt lgkmcnt(0)
	v_pk_mul_f32 v[8:9], v[8:9], v[210:211]
	v_pk_mul_f32 v[10:11], v[10:11], v[212:213]
	v_pk_mul_f32 v[12:13], v[12:13], v[248:249]
	v_pk_mul_f32 v[14:15], v[14:15], v[250:251]
	v_pk_mul_f32 v[24:25], v[24:25], v[210:211]
	v_pk_mul_f32 v[26:27], v[26:27], v[212:213]
	v_pk_mul_f32 v[28:29], v[28:29], v[248:249]
	v_pk_mul_f32 v[30:31], v[30:31], v[250:251]
	s_branch .Ldqc
.LBB0_525:
	s_mov_b32 s8, 0xaaaaaaaa
	s_mov_b32 s9, 0xaaaaaaaa
	v_cndmask_b32_e64 v162, v164, v165, s[8:9]
	v_cndmask_b32_e64 v64, v166, v167, s[8:9]
	v_cndmask_b32_e64 v161, v172, v173, s[8:9]
	v_cndmask_b32_e64 v65, v174, v175, s[8:9]
	s_mov_b32 s8, 0xcccccccc
	s_mov_b32 s9, 0xcccccccc
	v_cndmask_b32_e64 v162, v162, v64, s[8:9]
	v_cndmask_b32_e64 v161, v161, v65, s[8:9]
	v_mov_b32_e32 v64, v162
	v_mov_b32_e32 v65, v161
	s_nop 0
	v_permlane32_swap_b32_e32 v162, v64
	v_permlane32_swap_b32_e32 v161, v65
	s_and_saveexec_b64 s[8:9], s[4:5]
	s_cbranch_execz .LBB0_490
	v_add_f32_e32 v64, v162, v64
	v_add_f32_e32 v65, v161, v65
	ds_write2_b32 v180, v64, v65 offset0:64 offset1:96
	s_branch .LBB0_490
